# LDS bank conflicts: sample-attention PV partial outputs written with 4 conflict-free ds_write_b128 instead of 16 four-way-conflicting ds_write_b32
# baseline (speedup 1.0000x reference)
; #define LAS __attribute__((address_space(3)))
; __device__ __forceinline__ unsigned pk2(float lo, float hi) { return f2bf(lo) | (f2bf(hi) << 16); }
; __device__ __forceinline__ void attn_sample_unit(LAS unsigned char* lds, CArgsP a, int b, int h) {
;     ...
;         __syncthreads();
;         LAS float* red = SC;
; #pragma unroll
;         for (int t = 0; t < 16; ++t) red[(wid * 16 + t) * 64 + lane] = acc[t];
;         __syncthreads();
;         {
;             const int t = tid >> 5, d = 2 * (tid & 31);
;             float a0 = 0.f, a1 = 0.f;
; #pragma unroll
;             for (int w = 0; w < 8; ++w) { a0 += red[(w * 16 + t) * 64 + d]; a1 += red[(w * 16 + t) * 64 + d + 1]; }
;             *(unsigned*)(MIX + (size_t)(TP + 16 * b + t) * DM + h * 64 + d) = pk2(a0, a1);
.Lpv_noext:
	s_nop 9
	s_barrier
	v_mov_b32_e32 v16, v0
	v_mov_b32_e32 v17, v4
	v_mov_b32_e32 v18, v8
	v_mov_b32_e32 v19, v12
	v_mov_b32_e32 v20, v1
	v_mov_b32_e32 v21, v5
	v_mov_b32_e32 v22, v9
	v_mov_b32_e32 v23, v13
	v_mov_b32_e32 v24, v2
	v_mov_b32_e32 v25, v6
	v_mov_b32_e32 v26, v10
	v_mov_b32_e32 v27, v14
	v_mov_b32_e32 v28, v3
	v_mov_b32_e32 v29, v7
	v_mov_b32_e32 v30, v11
	v_mov_b32_e32 v31, v15
	ds_write_b128 v139, v[16:19] offset:0
	ds_write_b128 v139, v[20:23] offset:256
	ds_write_b128 v139, v[24:27] offset:512
	ds_write_b128 v139, v[28:31] offset:768
	s_movk_i32 s3, 0x7fff
	s_mov_b32 s5, 0
	s_lshl_b32 s4, s1, 1
	v_mov_b32_e32 v101, 0
	v_lshlrev_b32_e32 v0, 1, v164
	v_lshrrev_b32_e32 v14, 5, v164
	v_and_b32_e32 v15, 62, v0
	v_lshlrev_b32_e32 v0, 8, v14
	v_lshlrev_b32_e32 v1, 2, v15
	v_add3_u32 v0, 0, v0, v1
	v_add_u32_e32 v16, 0x100, v0
	s_waitcnt lgkmcnt(0)
	s_barrier
	ds_read2st64_b64 v[0:3], v16 offset0:16 offset1:24
	ds_read2st64_b64 v[4:7], v16 offset0:32 offset1:40
	ds_read2st64_b64 v[8:11], v16 offset0:48 offset1:56
	s_waitcnt lgkmcnt(2)
	v_pk_add_f32 v[0:1], v[0:1], 0 op_sel_hi:[1,0]
	s_nop 0
	v_pk_add_f32 v[12:13], v[0:1], v[2:3]
	ds_read2st64_b64 v[0:3], v16 offset0:64 offset1:72
	s_waitcnt lgkmcnt(2)
	v_pk_add_f32 v[4:5], v[12:13], v[4:5]
	s_nop 0
	v_pk_add_f32 v[4:5], v[4:5], v[6:7]
	s_waitcnt lgkmcnt(1)
	v_pk_add_f32 v[4:5], v[4:5], v[8:9]
	s_nop 0
	v_pk_add_f32 v[4:5], v[4:5], v[10:11]
	s_waitcnt lgkmcnt(0)
	v_pk_add_f32 v[0:1], v[4:5], v[0:1]
	s_nop 0
	v_pk_add_f32 v[0:1], v[0:1], v[2:3]
	v_mov_b32_e32 v2, 1
	v_and_b32_sdwa v3, v1, v2 dst_sel:DWORD dst_unused:UNUSED_PAD src0_sel:WORD_1 src1_sel:DWORD
	v_and_b32_sdwa v2, v0, v2 dst_sel:DWORD dst_unused:UNUSED_PAD src0_sel:WORD_1 src1_sel:DWORD
	v_add3_u32 v0, v0, v2, s3
	v_add3_u32 v1, v1, v3, s3
	v_lshrrev_b32_e32 v0, 16, v0
	s_mov_b32 s3, 0xffff0000
	v_and_or_b32 v4, v1, s3, v0
	v_add_u32_e32 v0, s0, v14
	v_bfrev_b32_e32 v1, 64
	v_lshl_add_u32 v0, v0, 11, v1
	v_mov_b32_e32 v1, v101
	v_lshl_add_u64 v[0:1], s[14:15], 0, v[0:1]
	v_lshl_add_u64 v[0:1], v[0:1], 0, s[4:5]
	v_lshlrev_b32_e32 v2, 1, v15
	v_mov_b32_e32 v3, v101
	v_lshl_add_u64 v[0:1], v[0:1], 0, v[2:3]
	v_add_co_u32_e32 v0, vcc, 0x2f00000, v0
	s_nop 1
	v_addc_co_u32_e32 v1, vcc, 0, v1, vcc
	global_store_dword v[0:1], v4, off
